# stack + attention segment prologue: previous block's 8 K/V row loads in flight together
# speedup vs baseline: 1.0076x; 1.0076x over previous
.LBB0_583:
	s_xor_b64 s[4:5], s[6:7], -1
	s_mov_b32 s6, s87
	s_ashr_i32 s7, s6, 31
	s_lshl_b64 s[6:7], s[6:7], 3
	s_add_u32 s6, s0, s6
	s_addc_u32 s7, s1, s7
	s_mov_b64 s[6:7], s[100:101]
	s_mov_b32 s8, 7
	s_mov_b32 s12, 8
	s_mov_b32 s16, s87
	s_waitcnt lgkmcnt(0)
	s_add_u32 s6, s6, s81
	s_addc_u32 s7, s7, 0
	s_add_u32 s6, s6, 0x9600000
	s_addc_u32 s7, s7, 0
	s_ashr_i32 s9, s8, 31
	s_lshl_b64 s[8:9], s[8:9], 3
	s_add_u32 s8, s0, s8
	s_addc_u32 s9, s1, s9
	s_load_dwordx2 s[8:9], s[8:9], 0x0
	s_mov_b32 s18, s87
	v_mov_b32_e32 v125, v0
	v_mov_b32_e32 v3, v4
	s_waitcnt lgkmcnt(0)
	s_add_u32 s8, s8, s2
	s_addc_u32 s9, s9, s3
	s_ashr_i32 s13, s12, 31
	s_lshl_b64 s[12:13], s[12:13], 3
	s_add_u32 s12, s0, s12
	s_addc_u32 s13, s1, s13
	s_load_dwordx2 s[12:13], s[12:13], 0x0
	s_waitcnt vmcnt(7)
	v_mov_b64_e32 v[78:79], s[6:7]
	v_mov_b32_e32 v121, v4
	s_waitcnt lgkmcnt(0)
	s_add_u32 s12, s12, s2
	s_addc_u32 s13, s13, s3
	s_ashr_i32 s17, s16, 31
	s_lshl_b64 s[16:17], s[16:17], 3
	s_add_u32 s16, s0, s16
	s_addc_u32 s17, s1, s17
	s_mov_b64 s[16:17], s[100:101]
	s_waitcnt lgkmcnt(0)
	s_add_u32 s16, s16, s81
	s_addc_u32 s17, s17, 0
	s_ashr_i32 s19, s18, 31
	s_lshl_b64 s[18:19], s[18:19], 3
	s_add_u32 s18, s0, s18
	s_addc_u32 s19, s1, s19
	s_mov_b64 s[18:19], s[100:101]
	s_waitcnt lgkmcnt(0)
	s_add_u32 s18, s18, s85
	v_lshlrev_b32_e32 v139, 3, v125
	v_and_b32_e32 v48, 0x78, v139
	v_bfe_u32 v129, v125, 4, 2
	v_lshlrev_b32_e32 v2, 2, v48
	s_addc_u32 s19, s19, 0
	global_load_dwordx4 v[6:9], v2, s[12:13] offset:16
	global_load_dwordx4 v[10:13], v2, s[12:13]
	v_lshlrev_b32_e32 v2, 5, v129
	s_lshl_b32 s12, s14, 1
	global_load_dwordx4 v[14:17], v2, s[8:9]
	global_load_dwordx4 v[18:21], v2, s[8:9] offset:16
	global_load_dwordx4 v[22:25], v2, s[8:9] offset:128
	global_load_dwordx4 v[26:29], v2, s[8:9] offset:144
	global_load_dwordx4 v[30:33], v2, s[8:9] offset:256
	global_load_dwordx4 v[34:37], v2, s[8:9] offset:272
	global_load_dwordx4 v[38:41], v2, s[8:9] offset:384
	global_load_dwordx4 v[42:45], v2, s[8:9] offset:400
	v_sub_co_u32_e64 v2, s[8:9], s55, 1
	s_add_i32 s58, s12, 7
	s_ashr_i32 s10, s11, 2
	v_lshlrev_b32_e32 v2, s58, v2
	s_and_b32 s20, s11, 3
	s_ashr_i32 s11, s10, 31
	v_add_u32_e32 v2, s56, v2
	v_ashrrev_i32_e32 v122, 4, v125
	s_lshl_b64 s[46:47], s[10:11], 12
	v_cndmask_b32_e64 v2, v2, 0, s[8:9]
	v_ashrrev_i32_e32 v123, 31, v122
	v_lshl_add_u64 v[54:55], s[46:47], 0, v[2:3]
	v_lshlrev_b64 v[110:111], s12, v[122:123]
	v_lshl_add_u64 v[2:3], v[110:111], 0, v[54:55]
	v_mad_u64_u32 v[46:47], s[10:11], v2, s77, v[78:79]
	v_mad_i32_i24 v47, v3, s77, v47
	s_lshl_b32 s86, s20, 8
	v_lshl_add_u64 v[46:47], v[46:47], 0, s[86:87]
	v_lshlrev_b32_e32 v2, 1, v48
	v_mov_b32_e32 v3, v4
	v_lshl_add_u64 v[50:51], v[46:47], 0, v[2:3]
	global_load_dwordx4 v[46:49], v[50:51], off offset:1024
	s_nop 0
	global_load_dwordx4 v[50:53], v[50:51], off offset:2048
	v_add_u32_e32 v186, 32, v122
	v_ashrrev_i32_e32 v187, 31, v186
	v_lshlrev_b64 v[112:113], s12, v[186:187]
	v_lshl_add_u64 v[186:187], v[112:113], 0, v[54:55]
	v_mad_u64_u32 v[188:189], s[10:11], v186, s77, v[78:79]
	v_mad_i32_i24 v189, v187, s77, v189
	v_lshl_add_u64 v[186:187], v[188:189], 0, s[86:87]
	v_lshl_add_u64 v[186:187], v[186:187], 0, v[2:3]
	global_load_dwordx4 v[162:165], v[186:187], off offset:1024
	global_load_dwordx4 v[166:169], v[186:187], off offset:2048
	v_add_u32_e32 v186, 64, v122
	v_ashrrev_i32_e32 v187, 31, v186
	v_lshlrev_b64 v[114:115], s12, v[186:187]
	v_lshl_add_u64 v[186:187], v[114:115], 0, v[54:55]
	v_mad_u64_u32 v[188:189], s[10:11], v186, s77, v[78:79]
	v_mad_i32_i24 v189, v187, s77, v189
	v_lshl_add_u64 v[186:187], v[188:189], 0, s[86:87]
	v_lshl_add_u64 v[186:187], v[186:187], 0, v[2:3]
	global_load_dwordx4 v[170:173], v[186:187], off offset:1024
	global_load_dwordx4 v[174:177], v[186:187], off offset:2048
	v_add_u32_e32 v186, 0x60, v122
	v_ashrrev_i32_e32 v187, 31, v186
	v_lshlrev_b64 v[116:117], s12, v[186:187]
	v_lshl_add_u64 v[186:187], v[116:117], 0, v[54:55]
	v_mad_u64_u32 v[188:189], s[10:11], v186, s77, v[78:79]
	v_mad_i32_i24 v189, v187, s77, v189
	v_lshl_add_u64 v[186:187], v[188:189], 0, s[86:87]
	v_lshl_add_u64 v[186:187], v[186:187], 0, v[2:3]
	global_load_dwordx4 v[178:181], v[186:187], off offset:1024
	global_load_dwordx4 v[182:185], v[186:187], off offset:2048
	v_lshlrev_b32_e32 v132, 1, v122
	v_and_b32_e32 v151, 15, v125
	v_lshlrev_b32_e32 v123, 8, v122
	v_xor_b32_e32 v124, v122, v125
	v_and_b32_e32 v132, 12, v132
	s_lshl_b32 s57, 0x80, s12
	v_lshlrev_b32_e32 v124, 4, v124
	v_and_b32_e32 v124, 0xf0, v124
	v_and_b32_e32 v120, 48, v125
	v_add_u32_e32 v124, 0, v124
	v_ashrrev_i32_e32 v5, 6, v125
	v_lshrrev_b32_e32 v126, 4, v125
	v_cmp_gt_i32_e64 s[22:23], 7, v5
	v_cmp_gt_i32_e64 s[24:25], 6, v5
	v_cmp_gt_i32_e64 s[26:27], 5, v5
	v_cmp_gt_i32_e64 s[28:29], 4, v5
	v_cmp_gt_i32_e64 s[30:31], 3, v5
	v_cmp_gt_i32_e64 s[34:35], 2, v5
	v_cmp_gt_i32_e64 s[36:37], 1, v5
	v_cmp_gt_i32_e64 s[38:39], 0, v5
	s_waitcnt vmcnt(7)
	v_cndmask_b32_e64 v131, v46, 0, s[8:9]
	v_cndmask_b32_e64 v128, v47, 0, s[8:9]
	v_cndmask_b32_e64 v127, v49, 0, s[8:9]
	v_cndmask_b32_e64 v130, v48, 0, s[8:9]
	s_waitcnt vmcnt(6)
	v_cndmask_b32_e64 v103, v51, 0, s[8:9]
	v_cndmask_b32_e64 v102, v50, 0, s[8:9]
	v_cndmask_b32_e64 v105, v53, 0, s[8:9]
	v_cndmask_b32_e64 v104, v52, 0, s[8:9]
	v_and_b32_e32 v135, 0xffff0000, v130
	v_and_b32_e32 v134, 0xffff0000, v131
	v_and_b32_e32 v141, 0xffff0000, v127
	v_and_b32_e32 v140, 0xffff0000, v128
	v_lshlrev_b32_e32 v133, 16, v130
	v_lshlrev_b32_e32 v137, 16, v127
	v_lshlrev_b32_e32 v136, 16, v128
	v_pk_mul_f32 v[142:143], v[140:141], v[140:141]
	s_waitcnt vmcnt(5)
	v_cndmask_b32_e64 v146, v162, 0, s[8:9]
	v_cndmask_b32_e64 v144, v163, 0, s[8:9]
	v_cndmask_b32_e64 v138, v165, 0, s[8:9]
	v_cndmask_b32_e64 v145, v164, 0, s[8:9]
	s_waitcnt vmcnt(4)
	v_cndmask_b32_e64 v99, v167, 0, s[8:9]
	v_cndmask_b32_e64 v98, v166, 0, s[8:9]
	v_cndmask_b32_e64 v101, v169, 0, s[8:9]
	v_cndmask_b32_e64 v100, v168, 0, s[8:9]
	v_pk_fma_f32 v[142:143], v[136:137], v[136:137], v[142:143]
	s_waitcnt vmcnt(3)
	v_cndmask_b32_e64 v150, v170, 0, s[8:9]
	v_cndmask_b32_e64 v148, v171, 0, s[8:9]
	v_cndmask_b32_e64 v147, v173, 0, s[8:9]
	v_cndmask_b32_e64 v149, v172, 0, s[8:9]
	s_waitcnt vmcnt(2)
	v_cndmask_b32_e64 v95, v175, 0, s[8:9]
	v_cndmask_b32_e64 v94, v174, 0, s[8:9]
	v_cndmask_b32_e64 v97, v177, 0, s[8:9]
	v_cndmask_b32_e64 v96, v176, 0, s[8:9]
	v_and_b32_e32 v122, 1, v122
	v_bitop3_b32 v122, v132, v151, v122 bitop3:0x36
	v_lshlrev_b32_e32 v132, 16, v131
	v_pk_mul_f32 v[130:131], v[134:135], v[134:135]
	s_waitcnt vmcnt(1)
	v_cndmask_b32_e64 v152, v181, 0, s[8:9]
	v_pk_fma_f32 v[130:131], v[132:133], v[132:133], v[130:131]
	s_waitcnt vmcnt(0)
	v_cndmask_b32_e64 v109, v185, 0, s[8:9]
	v_cndmask_b32_e64 v108, v184, 0, s[8:9]
	v_cndmask_b32_e64 v107, v183, 0, s[8:9]
	v_cndmask_b32_e64 v106, v182, 0, s[8:9]
	v_cndmask_b32_e64 v153, v179, 0, s[8:9]
	v_cndmask_b32_e64 v154, v180, 0, s[8:9]
	v_cndmask_b32_e64 v155, v178, 0, s[8:9]
	s_lshl_b32 s8, s55, s58
	v_pk_add_f32 v[130:131], v[130:131], v[142:143]
	v_ashrrev_i32_e32 v46, 2, v125
	s_add_i32 s8, s8, s56
	v_add_f32_e32 v127, v130, v131
	v_bfi_b32 v46, -16, v46, v125
	s_add_u32 s8, s46, s8
	v_add_f32_dpp v127, v127, v127 row_ror:8 row_mask:0xf bank_mask:0xf bound_ctrl:1
	v_ashrrev_i32_e32 v47, 31, v46
	s_addc_u32 s9, s47, 0
	v_add_f32_dpp v127, v127, v127 row_ror:4 row_mask:0xf bank_mask:0xf bound_ctrl:1
	v_lshlrev_b64 v[118:119], s12, v[46:47]
	v_lshl_add_u64 v[46:47], v[110:111], 0, s[8:9]
	v_add_f32_dpp v127, v127, v127 row_ror:2 row_mask:0xf bank_mask:0xf bound_ctrl:1
	v_mad_u64_u32 v[48:49], s[10:11], v46, s77, v[78:79]
	s_nop 0
	v_add_f32_dpp v127, v127, v127 row_ror:1 row_mask:0xf bank_mask:0xf bound_ctrl:1
	v_mad_i32_i24 v49, v47, s77, v49
	v_fmamk_f32 v127, v127, 0x3c000000, v236
	v_lshl_add_u64 v[46:47], v[48:49], 0, s[86:87]
	v_rsq_f32_e32 v127, v127
	v_lshl_add_u64 v[50:51], v[46:47], 0, v[2:3]
	global_load_dwordx4 v[46:49], v[50:51], off offset:1024
	s_nop 0
	global_load_dwordx4 v[50:53], v[50:51], off offset:2048
	v_lshl_add_u64 v[54:55], v[112:113], 0, s[8:9]
	v_mul_f32_e32 v128, v127, v132
	v_mul_f32_e32 v130, v127, v134
	v_mul_f32_e32 v128, v10, v128
	v_mul_f32_e32 v130, v11, v130
	v_cvt_pk_bf16_f32 v130, v128, v130
	v_mul_f32_e32 v128, v127, v136
	v_mul_f32_e32 v131, v127, v140
	v_mul_f32_e32 v128, v12, v128
	v_mul_f32_e32 v131, v13, v131
	v_lshl_add_u64 v[62:63], v[114:115], 0, s[8:9]
	v_lshl_add_u64 v[70:71], v[116:117], 0, s[8:9]
	v_lshl_add_u64 v[80:81], v[118:119], 0, s[8:9]
	v_cvt_pk_bf16_f32 v131, v128, v131
	v_mul_f32_e32 v128, v127, v133
	v_mul_f32_e32 v132, v127, v135
	v_mad_u64_u32 v[56:57], s[10:11], v54, s77, v[78:79]
	v_mad_u64_u32 v[64:65], s[10:11], v62, s77, v[78:79]
	v_mad_u64_u32 v[72:73], s[10:11], v70, s77, v[78:79]
	v_mad_u64_u32 v[78:79], s[8:9], v80, s77, v[78:79]
	v_mul_f32_e32 v128, v6, v128
	v_mul_f32_e32 v132, v7, v132
	v_mad_i32_i24 v57, v55, s77, v57
	v_mad_i32_i24 v65, v63, s77, v65
	v_mad_i32_i24 v73, v71, s77, v73
	v_mad_i32_i24 v79, v81, s77, v79
	v_cvt_pk_bf16_f32 v132, v128, v132
	v_mul_f32_e32 v128, v127, v137
	v_mul_f32_e32 v127, v127, v141
	v_lshl_add_u64 v[54:55], v[56:57], 0, s[86:87]
	v_lshl_add_u64 v[62:63], v[64:65], 0, s[86:87]
	v_lshl_add_u64 v[70:71], v[72:73], 0, s[86:87]
	v_lshl_add_u64 v[78:79], v[78:79], 0, s[86:87]
	s_add_i32 s54, 0, 0x10000
	v_mul_f32_e32 v127, v9, v127
	v_lshl_add_u64 v[58:59], v[54:55], 0, v[2:3]
	v_lshl_add_u64 v[66:67], v[62:63], 0, v[2:3]
	v_lshl_add_u64 v[74:75], v[70:71], 0, v[2:3]
	v_lshl_add_u64 v[90:91], v[78:79], 0, v[120:121]
	v_lshl_add_u32 v122, v122, 4, s54
	v_mul_f32_e32 v128, v8, v128
	v_cvt_pk_bf16_f32 v133, v128, v127
	v_add_u32_e32 v127, v124, v123
	global_load_dwordx4 v[54:57], v[58:59], off offset:1024
	s_nop 0
	global_load_dwordx4 v[58:61], v[58:59], off offset:2048
	s_nop 0
	global_load_dwordx4 v[62:65], v[66:67], off offset:1024
	s_nop 0
	global_load_dwordx4 v[66:69], v[66:67], off offset:2048
	s_nop 0
	global_load_dwordx4 v[70:73], v[74:75], off offset:1024
	s_nop 0
	global_load_dwordx4 v[74:77], v[74:75], off offset:2048
	s_nop 0
	global_load_dwordx4 v[78:81], v[90:91], off
	global_load_dwordx4 v[82:85], v[90:91], off offset:64
	global_load_dwordx4 v[86:89], v[90:91], off offset:128
	s_nop 0
	global_load_dwordx4 v[90:93], v[90:91], off offset:192
	ds_write_b128 v127, v[130:133] offset:32768
	v_add_u32_e32 v128, v122, v123
	v_and_b32_e32 v131, 0xffff0000, v145
	v_and_b32_e32 v130, 0xffff0000, v146
	v_and_b32_e32 v135, 0xffff0000, v138
	v_and_b32_e32 v134, 0xffff0000, v144
	ds_write_b128 v128, v[102:105] offset:32768
	v_lshlrev_b32_e32 v105, 16, v145
	v_lshlrev_b32_e32 v104, 16, v146
	v_lshlrev_b32_e32 v133, 16, v138
	v_lshlrev_b32_e32 v132, 16, v144
	v_pk_mul_f32 v[102:103], v[130:131], v[130:131]
	v_pk_mul_f32 v[136:137], v[134:135], v[134:135]
	v_pk_fma_f32 v[102:103], v[104:105], v[104:105], v[102:103]
	v_pk_fma_f32 v[136:137], v[132:133], v[132:133], v[136:137]
	s_add_i32 s59, s55, s15
	v_pk_add_f32 v[102:103], v[102:103], v[136:137]
	s_add_u32 s50, s6, s86
	v_add_f32_e32 v102, v102, v103
	s_addc_u32 s51, s7, 0
	s_add_u32 s6, s16, s86
	v_add_f32_dpp v102, v102, v102 row_ror:8 row_mask:0xf bank_mask:0xf bound_ctrl:1
	s_addc_u32 s7, s17, 0
	s_lshl_b32 s10, s14, 18
	v_add_f32_dpp v102, v102, v102 row_ror:4 row_mask:0xf bank_mask:0xf bound_ctrl:1
	s_lshl_b32 s11, s20, 16
	s_lshl_b32 s86, s14, 12
	v_add_f32_dpp v102, v102, v102 row_ror:2 row_mask:0xf bank_mask:0xf bound_ctrl:1
	s_or_b32 s10, s11, s10
	s_add_u32 s10, s18, s10
	v_add_f32_dpp v102, v102, v102 row_ror:1 row_mask:0xf bank_mask:0xf bound_ctrl:1
	v_fmamk_f32 v102, v102, 0x3c000000, v236
	v_rsq_f32_e32 v136, v102
	s_addc_u32 s11, s19, 0
	v_cmp_eq_u32_e64 s[8:9], 0, v129
	s_add_u32 s48, s10, 0x400000
	v_mul_f32_e32 v102, v136, v104
	v_mul_f32_e32 v103, v136, v130
	v_mul_f32_e32 v102, v10, v102
	v_mul_f32_e32 v103, v11, v103
	v_cvt_pk_bf16_f32 v102, v102, v103
	v_mul_f32_e32 v103, v136, v132
	v_mul_f32_e32 v104, v136, v134
	v_mul_f32_e32 v103, v12, v103
	v_mul_f32_e32 v104, v13, v104
	v_cvt_pk_bf16_f32 v103, v103, v104
	v_mul_f32_e32 v104, v136, v105
	v_mul_f32_e32 v105, v136, v131
	v_mul_f32_e32 v104, v6, v104
	v_mul_f32_e32 v105, v7, v105
	v_cvt_pk_bf16_f32 v104, v104, v105
	v_mul_f32_e32 v105, v136, v133
	v_mul_f32_e32 v105, v8, v105
	v_mul_f32_e32 v130, v136, v135
	v_mul_f32_e32 v130, v9, v130
	v_cvt_pk_bf16_f32 v105, v105, v130
	ds_write_b128 v127, v[102:105] offset:40960
	ds_write_b128 v128, v[98:101] offset:40960
	v_and_b32_e32 v103, 0xffff0000, v149
	v_and_b32_e32 v102, 0xffff0000, v150
	v_and_b32_e32 v131, 0xffff0000, v147
	v_and_b32_e32 v130, 0xffff0000, v148
	v_lshlrev_b32_e32 v101, 16, v149
	v_lshlrev_b32_e32 v100, 16, v150
	v_lshlrev_b32_e32 v105, 16, v147
	v_lshlrev_b32_e32 v104, 16, v148
	v_pk_mul_f32 v[98:99], v[102:103], v[102:103]
	v_pk_mul_f32 v[132:133], v[130:131], v[130:131]
	v_pk_fma_f32 v[98:99], v[100:101], v[100:101], v[98:99]
	v_pk_fma_f32 v[132:133], v[104:105], v[104:105], v[132:133]
	s_addc_u32 s49, s11, 0
	v_pk_add_f32 v[98:99], v[98:99], v[132:133]
	s_lshl_b32 s60, s55, 7
	v_add_f32_e32 v98, v98, v99
	v_cmp_gt_i32_e64 s[14:15], 8, v5
	v_and_b32_e32 v138, 8, v139
	v_add_f32_dpp v98, v98, v98 row_ror:8 row_mask:0xf bank_mask:0xf bound_ctrl:1
	v_bitop3_b32 v139, v139, 8, v139 bitop3:0xc
	s_sub_i32 s61, 0, s60
	v_add_f32_dpp v98, v98, v98 row_ror:4 row_mask:0xf bank_mask:0xf bound_ctrl:1
	s_nop 1
	v_add_f32_dpp v98, v98, v98 row_ror:2 row_mask:0xf bank_mask:0xf bound_ctrl:1
	s_nop 1
	v_add_f32_dpp v98, v98, v98 row_ror:1 row_mask:0xf bank_mask:0xf bound_ctrl:1
	v_fmamk_f32 v98, v98, 0x3c000000, v236
	v_rsq_f32_e32 v132, v98
	s_nop 0
	v_mul_f32_e32 v98, v132, v100
	v_mul_f32_e32 v99, v132, v102
	v_mul_f32_e32 v98, v10, v98
	v_mul_f32_e32 v99, v11, v99
	v_cvt_pk_bf16_f32 v98, v98, v99
	v_mul_f32_e32 v99, v132, v104
	v_mul_f32_e32 v100, v132, v130
	v_mul_f32_e32 v99, v12, v99
	v_mul_f32_e32 v100, v13, v100
	v_cvt_pk_bf16_f32 v99, v99, v100
	v_mul_f32_e32 v100, v132, v101
	v_mul_f32_e32 v101, v132, v103
	v_mul_f32_e32 v100, v6, v100
	v_mul_f32_e32 v101, v7, v101
	v_cvt_pk_bf16_f32 v100, v100, v101
	v_mul_f32_e32 v101, v132, v105
	v_mul_f32_e32 v101, v8, v101
	v_mul_f32_e32 v102, v132, v131
	v_mul_f32_e32 v102, v9, v102
	v_cvt_pk_bf16_f32 v101, v101, v102
	ds_write_b128 v127, v[98:101] offset:49152
	ds_write_b128 v128, v[94:97] offset:49152
	v_and_b32_e32 v99, 0xffff0000, v154
	v_and_b32_e32 v98, 0xffff0000, v155
	v_and_b32_e32 v103, 0xffff0000, v152
	v_and_b32_e32 v102, 0xffff0000, v153
	v_lshlrev_b32_e32 v97, 16, v154
	v_lshlrev_b32_e32 v96, 16, v155
	v_lshlrev_b32_e32 v101, 16, v152
	v_lshlrev_b32_e32 v100, 16, v153
	v_pk_mul_f32 v[94:95], v[98:99], v[98:99]
	v_pk_mul_f32 v[104:105], v[102:103], v[102:103]
	v_pk_fma_f32 v[94:95], v[96:97], v[96:97], v[94:95]
	v_pk_fma_f32 v[104:105], v[100:101], v[100:101], v[104:105]
	s_nop 0
	v_pk_add_f32 v[94:95], v[94:95], v[104:105]
	s_nop 0
	v_add_f32_e32 v94, v94, v95
	s_nop 1
	v_add_f32_dpp v94, v94, v94 row_ror:8 row_mask:0xf bank_mask:0xf bound_ctrl:1
	s_nop 1
	v_add_f32_dpp v94, v94, v94 row_ror:4 row_mask:0xf bank_mask:0xf bound_ctrl:1
	s_nop 1
	v_add_f32_dpp v94, v94, v94 row_ror:2 row_mask:0xf bank_mask:0xf bound_ctrl:1
	s_nop 1
	v_add_f32_dpp v94, v94, v94 row_ror:1 row_mask:0xf bank_mask:0xf bound_ctrl:1
	v_fmamk_f32 v94, v94, 0x3c000000, v236
	v_rsq_f32_e32 v104, v94
	s_nop 0
	v_mul_f32_e32 v94, v104, v96
	v_mul_f32_e32 v95, v104, v98
	v_mul_f32_e32 v94, v10, v94
	v_mul_f32_e32 v95, v11, v95
	v_cvt_pk_bf16_f32 v94, v94, v95
	v_mul_f32_e32 v95, v104, v100
	v_mul_f32_e32 v96, v104, v102
	v_mul_f32_e32 v95, v12, v95
	v_mul_f32_e32 v96, v13, v96
	v_cvt_pk_bf16_f32 v95, v95, v96
	v_mul_f32_e32 v96, v104, v97
	v_mul_f32_e32 v97, v104, v99
	v_mul_f32_e32 v96, v6, v96
	v_mul_f32_e32 v97, v7, v97
	v_cvt_pk_bf16_f32 v96, v96, v97
	v_mul_f32_e32 v97, v104, v101
	v_mul_f32_e32 v98, v104, v103
	v_mul_f32_e32 v97, v8, v97
	v_mul_f32_e32 v98, v9, v98
	v_cvt_pk_bf16_f32 v97, v97, v98
	s_waitcnt vmcnt(11)
	v_and_b32_e32 v99, 0xffff0000, v48
	v_and_b32_e32 v98, 0xffff0000, v46
	v_and_b32_e32 v103, 0xffff0000, v49
	v_and_b32_e32 v102, 0xffff0000, v47
	ds_write_b128 v127, v[94:97] offset:57344
	ds_write_b128 v128, v[106:109] offset:57344
	v_lshlrev_b32_e32 v97, 16, v48
	v_lshlrev_b32_e32 v96, 16, v46
	v_lshlrev_b32_e32 v101, 16, v49
	v_lshlrev_b32_e32 v100, 16, v47
	v_pk_mul_f32 v[94:95], v[98:99], v[98:99]
	v_pk_mul_f32 v[104:105], v[102:103], v[102:103]
	v_pk_fma_f32 v[94:95], v[96:97], v[96:97], v[94:95]
	v_pk_fma_f32 v[104:105], v[100:101], v[100:101], v[104:105]
	s_nop 0
	v_pk_add_f32 v[94:95], v[94:95], v[104:105]
	s_nop 0
	v_add_f32_e32 v94, v94, v95
	s_nop 1
	v_add_f32_dpp v94, v94, v94 row_ror:8 row_mask:0xf bank_mask:0xf bound_ctrl:1
	s_nop 1
	v_add_f32_dpp v94, v94, v94 row_ror:4 row_mask:0xf bank_mask:0xf bound_ctrl:1
	s_nop 1
	v_add_f32_dpp v94, v94, v94 row_ror:2 row_mask:0xf bank_mask:0xf bound_ctrl:1
	s_nop 1
	v_add_f32_dpp v94, v94, v94 row_ror:1 row_mask:0xf bank_mask:0xf bound_ctrl:1
	v_fmamk_f32 v94, v94, 0x3c000000, v236
	v_rsq_f32_e32 v104, v94
	s_nop 0
	v_mul_f32_e32 v94, v104, v96
	v_mul_f32_e32 v95, v104, v98
	v_mul_f32_e32 v94, v10, v94
	v_mul_f32_e32 v95, v11, v95
	v_cvt_pk_bf16_f32 v94, v94, v95
	v_mul_f32_e32 v95, v104, v100
	v_mul_f32_e32 v96, v104, v102
	v_mul_f32_e32 v95, v12, v95
	v_mul_f32_e32 v96, v13, v96
	v_cvt_pk_bf16_f32 v95, v95, v96
	v_mul_f32_e32 v96, v104, v97
	v_mul_f32_e32 v97, v104, v99
	v_mul_f32_e32 v96, v6, v96
	v_mul_f32_e32 v97, v7, v97
	v_cvt_pk_bf16_f32 v96, v96, v97
	v_mul_f32_e32 v97, v104, v101
	v_mul_f32_e32 v98, v104, v103
	v_mul_f32_e32 v97, v8, v97
	v_mul_f32_e32 v98, v9, v98
	v_cvt_pk_bf16_f32 v97, v97, v98
	s_waitcnt vmcnt(9)
	v_and_b32_e32 v99, 0xffff0000, v56
	v_and_b32_e32 v98, 0xffff0000, v54
	v_and_b32_e32 v103, 0xffff0000, v57
	v_and_b32_e32 v102, 0xffff0000, v55
	ds_write_b128 v127, v[94:97]
	ds_write_b128 v128, v[50:53]
	v_lshlrev_b32_e32 v97, 16, v56
	v_lshlrev_b32_e32 v96, 16, v54
	v_lshlrev_b32_e32 v101, 16, v57
	v_lshlrev_b32_e32 v100, 16, v55
	v_pk_mul_f32 v[94:95], v[98:99], v[98:99]
	v_pk_mul_f32 v[104:105], v[102:103], v[102:103]
	v_pk_fma_f32 v[94:95], v[96:97], v[96:97], v[94:95]
	v_pk_fma_f32 v[104:105], v[100:101], v[100:101], v[104:105]
	s_nop 0
	v_pk_add_f32 v[94:95], v[94:95], v[104:105]
	s_nop 0
	v_add_f32_e32 v94, v94, v95
	s_nop 1
	v_add_f32_dpp v94, v94, v94 row_ror:8 row_mask:0xf bank_mask:0xf bound_ctrl:1
	s_nop 1
	v_add_f32_dpp v94, v94, v94 row_ror:4 row_mask:0xf bank_mask:0xf bound_ctrl:1
	s_nop 1
	v_add_f32_dpp v94, v94, v94 row_ror:2 row_mask:0xf bank_mask:0xf bound_ctrl:1
	s_nop 1
	v_add_f32_dpp v94, v94, v94 row_ror:1 row_mask:0xf bank_mask:0xf bound_ctrl:1
	v_fmamk_f32 v94, v94, 0x3c000000, v236
	v_rsq_f32_e32 v104, v94
	s_nop 0
	v_mul_f32_e32 v94, v104, v96
	v_mul_f32_e32 v95, v104, v98
	v_mul_f32_e32 v94, v10, v94
	v_mul_f32_e32 v95, v11, v95
	v_cvt_pk_bf16_f32 v94, v94, v95
	v_mul_f32_e32 v95, v104, v100
	v_mul_f32_e32 v96, v104, v102
	v_mul_f32_e32 v95, v12, v95
	v_mul_f32_e32 v96, v13, v96
	v_cvt_pk_bf16_f32 v95, v95, v96
	v_mul_f32_e32 v96, v104, v97
	v_mul_f32_e32 v97, v104, v99
	v_mul_f32_e32 v96, v6, v96
	v_mul_f32_e32 v97, v7, v97
	v_cvt_pk_bf16_f32 v96, v96, v97
	v_mul_f32_e32 v97, v104, v101
	v_mul_f32_e32 v98, v104, v103
	v_mul_f32_e32 v97, v8, v97
	v_mul_f32_e32 v98, v9, v98
	v_cvt_pk_bf16_f32 v97, v97, v98
	s_waitcnt vmcnt(7)
	v_and_b32_e32 v99, 0xffff0000, v64
	v_and_b32_e32 v98, 0xffff0000, v62
	v_and_b32_e32 v103, 0xffff0000, v65
	v_and_b32_e32 v102, 0xffff0000, v63
	ds_write_b128 v127, v[94:97] offset:8192
	ds_write_b128 v128, v[58:61] offset:8192
	v_lshlrev_b32_e32 v97, 16, v64
	v_lshlrev_b32_e32 v96, 16, v62
	v_lshlrev_b32_e32 v101, 16, v65
	v_lshlrev_b32_e32 v100, 16, v63
	v_pk_mul_f32 v[94:95], v[98:99], v[98:99]
	v_pk_mul_f32 v[104:105], v[102:103], v[102:103]
	v_pk_fma_f32 v[94:95], v[96:97], v[96:97], v[94:95]
	v_pk_fma_f32 v[104:105], v[100:101], v[100:101], v[104:105]
	s_nop 0
	v_pk_add_f32 v[94:95], v[94:95], v[104:105]
	s_nop 0
	v_add_f32_e32 v94, v94, v95
	s_nop 1
	v_add_f32_dpp v94, v94, v94 row_ror:8 row_mask:0xf bank_mask:0xf bound_ctrl:1
	s_nop 1
	v_add_f32_dpp v94, v94, v94 row_ror:4 row_mask:0xf bank_mask:0xf bound_ctrl:1
	s_nop 1
	v_add_f32_dpp v94, v94, v94 row_ror:2 row_mask:0xf bank_mask:0xf bound_ctrl:1
	s_nop 1
	v_add_f32_dpp v94, v94, v94 row_ror:1 row_mask:0xf bank_mask:0xf bound_ctrl:1
	v_fmamk_f32 v94, v94, 0x3c000000, v236
	v_rsq_f32_e32 v104, v94
	s_nop 0
	v_mul_f32_e32 v94, v104, v96
	v_mul_f32_e32 v95, v104, v98
	v_mul_f32_e32 v94, v10, v94
	v_mul_f32_e32 v95, v11, v95
	v_cvt_pk_bf16_f32 v94, v94, v95
	v_mul_f32_e32 v95, v104, v100
	v_mul_f32_e32 v96, v104, v102
	v_mul_f32_e32 v95, v12, v95
	v_mul_f32_e32 v96, v13, v96
	v_cvt_pk_bf16_f32 v95, v95, v96
	v_mul_f32_e32 v96, v104, v97
	v_mul_f32_e32 v97, v104, v99
	v_mul_f32_e32 v96, v6, v96
	v_mul_f32_e32 v97, v7, v97
	v_cvt_pk_bf16_f32 v96, v96, v97
	v_mul_f32_e32 v97, v104, v101
	v_mul_f32_e32 v98, v104, v103
	v_mul_f32_e32 v97, v8, v97
	v_mul_f32_e32 v98, v9, v98
	v_cvt_pk_bf16_f32 v97, v97, v98
	s_waitcnt vmcnt(5)
	v_and_b32_e32 v99, 0xffff0000, v72
	v_and_b32_e32 v98, 0xffff0000, v70
	v_and_b32_e32 v103, 0xffff0000, v73
	v_and_b32_e32 v102, 0xffff0000, v71
	ds_write_b128 v127, v[94:97] offset:16384
	ds_write_b128 v128, v[66:69] offset:16384
	v_lshlrev_b32_e32 v97, 16, v72
	v_lshlrev_b32_e32 v96, 16, v70
	v_lshlrev_b32_e32 v101, 16, v73
	v_lshlrev_b32_e32 v100, 16, v71
	v_pk_mul_f32 v[94:95], v[98:99], v[98:99]
	v_pk_mul_f32 v[104:105], v[102:103], v[102:103]
	v_pk_fma_f32 v[94:95], v[96:97], v[96:97], v[94:95]
	v_pk_fma_f32 v[104:105], v[100:101], v[100:101], v[104:105]
	s_nop 0
	v_pk_add_f32 v[94:95], v[94:95], v[104:105]
	s_nop 0
	v_add_f32_e32 v94, v94, v95
	s_nop 1
	v_add_f32_dpp v94, v94, v94 row_ror:8 row_mask:0xf bank_mask:0xf bound_ctrl:1
	s_nop 1
	v_add_f32_dpp v94, v94, v94 row_ror:4 row_mask:0xf bank_mask:0xf bound_ctrl:1
	s_nop 1
	v_add_f32_dpp v94, v94, v94 row_ror:2 row_mask:0xf bank_mask:0xf bound_ctrl:1
	s_nop 1
	v_add_f32_dpp v94, v94, v94 row_ror:1 row_mask:0xf bank_mask:0xf bound_ctrl:1
	v_fmamk_f32 v94, v94, 0x3c000000, v236
	v_rsq_f32_e32 v104, v94
	s_nop 0
	v_mul_f32_e32 v94, v104, v96
	v_mul_f32_e32 v95, v104, v98
	v_mul_f32_e32 v94, v10, v94
	v_mul_f32_e32 v95, v11, v95
	v_cvt_pk_bf16_f32 v94, v94, v95
	v_mul_f32_e32 v95, v104, v100
	v_mul_f32_e32 v96, v104, v102
	v_mul_f32_e32 v95, v12, v95
	v_mul_f32_e32 v96, v13, v96
	v_cvt_pk_bf16_f32 v95, v95, v96
	v_mul_f32_e32 v96, v104, v97
	v_mul_f32_e32 v97, v104, v99
	v_mul_f32_e32 v96, v6, v96
	v_mul_f32_e32 v97, v7, v97
	v_cvt_pk_bf16_f32 v96, v96, v97
	v_mul_f32_e32 v97, v104, v101
	v_mul_f32_e32 v97, v8, v97
	v_mul_f32_e32 v98, v104, v103
	v_mul_f32_e32 v98, v9, v98
	v_cvt_pk_bf16_f32 v97, v97, v98
	ds_write_b128 v127, v[94:97] offset:24576
	s_waitcnt vmcnt(4)
	ds_write_b128 v128, v[74:77] offset:24576
	v_lshlrev_b32_e32 v96, 4, v5
	v_or_b32_e32 v94, v96, v151
	v_ashrrev_i32_e32 v95, 31, v94
	v_lshlrev_b32_e32 v97, 2, v129
	v_lshlrev_b64 v[94:95], s12, v[94:95]
	v_or_b32_e32 v108, 1, v97
	v_lshl_add_u64 v[102:103], v[94:95], 0, s[46:47]
	v_lshlrev_b32_e32 v94, 4, v129
	v_mov_b32_e32 v95, v4
	v_add_u32_e32 v153, 0x80, v96
	v_cmp_lt_u32_e64 s[16:17], v108, v151
	v_or_b32_e32 v108, 2, v97
	v_or_b32_e32 v109, 3, v97
	v_lshl_add_u64 v[94:95], s[6:7], 0, v[94:95]
	s_mov_b64 s[6:7], 0xaa00000
	v_add_u32_e32 v154, 0x70, v96
	v_cmp_lt_u32_e64 s[18:19], v108, v151
	v_cmp_lt_u32_e64 s[20:21], v109, v151
	v_cmp_gt_u32_e64 s[42:43], v108, v151
	v_cmp_gt_u32_e64 s[44:45], v109, v151
	v_lshl_add_u64 v[108:109], s[50:51], 0, v[2:3]
	v_and_b32_e32 v2, 0xffffff80, v153
	v_lshl_add_u64 v[106:107], v[94:95], 0, s[6:7]
	v_and_b32_e32 v94, 16, v125
	v_add_u32_e32 v155, 0x60, v96
	v_and_b32_e32 v137, 0x70, v153
	v_add_u32_e32 v153, 0xffffff80, v2
	v_and_b32_e32 v2, 0xffffff80, v154
	v_cmp_eq_u32_e64 s[6:7], 0, v94
	v_bitop3_b32 v94, v126, v151, 3 bitop3:0x6c
	v_add_u32_e32 v101, 0x50, v96
	v_and_b32_e32 v136, 0x70, v154
	v_add_u32_e32 v154, 0xffffff80, v2
	v_and_b32_e32 v2, 0xffffff80, v155
	v_lshlrev_b32_e32 v126, 4, v94
	v_bitop3_b32 v94, v129, v151, 4 bitop3:0x36
	v_add_u32_e32 v100, 64, v96
	v_and_b32_e32 v135, 0x70, v155
	v_add_u32_e32 v155, 0xffffff80, v2
	v_and_b32_e32 v2, 0xffffff80, v101
	v_lshlrev_b32_e32 v127, 4, v94
	v_bitop3_b32 v94, v129, v151, 8 bitop3:0x36
	v_add_u32_e32 v99, 48, v96
	v_add_u32_e32 v156, 0xffffff80, v2
	v_and_b32_e32 v2, 0xffffff80, v100
	v_lshlrev_b32_e32 v128, 4, v94
	v_bitop3_b32 v94, v129, v151, 12 bitop3:0x36
	v_add_u32_e32 v95, 32, v96
	v_add_u32_e32 v157, 0xffffff80, v2
	v_and_b32_e32 v2, 0xffffff80, v99
	v_lshlrev_b32_e32 v129, 4, v94
	v_add_u32_e32 v94, 16, v96
	v_add_u32_e32 v158, 0xffffff80, v2
	v_and_b32_e32 v2, 0xffffff80, v95
	v_add_u32_e32 v159, 0xffffff80, v2
	v_and_b32_e32 v2, 0xffffff80, v94
	v_lshl_add_u64 v[104:105], s[50:51], 0, v[120:121]
	v_bfe_u32 v98, v125, 2, 2
	v_and_b32_e32 v120, 3, v125
	v_and_b32_e32 v125, 0x70, v96
	v_and_b32_e32 v130, 0x70, v94
	v_and_b32_e32 v131, 0x70, v95
	v_and_b32_e32 v132, 0x70, v99
	v_and_b32_e32 v133, 0x70, v100
	v_and_b32_e32 v134, 0x70, v101
	v_add_u32_e32 v160, 0xffffff80, v2
	v_and_b32_e32 v2, 0xffffff80, v96
	s_lshl_b32 s50, s55, 15
	v_bfe_u32 v121, v151, 2, 1
	v_cmp_gt_u32_e64 s[10:11], v97, v151
	v_cmp_lt_u32_e64 s[12:13], v97, v151
	v_cmp_ge_u32_e64 s[40:41], v97, v151
	v_or_b32_e32 v140, 4, v120
	v_or_b32_e32 v141, 8, v120
	v_or_b32_e32 v142, 12, v120
	v_or_b32_e32 v143, v125, v151
	v_or_b32_e32 v144, v130, v151
	v_or_b32_e32 v145, v131, v151
	v_or_b32_e32 v146, v151, v132
	v_or_b32_e32 v147, v133, v151
	v_or_b32_e32 v148, v151, v134
	v_or_b32_e32 v149, v135, v151
	v_or_b32_e32 v150, v151, v136
	v_or_b32_e32 v151, v137, v151
	v_or_b32_e32 v152, v97, v98
	v_add_u32_e32 v161, 0xffffff80, v2
	s_add_i32 s62, s50, 0x8000
	s_branch .LBB0_585
